# GEMM main loops software-pipelined: next k-step global loads issued before the MFMAs into a dedicated register slab (saddr addressing)
# baseline (speedup 1.0000x reference)
; template <class Epi>
; __device__ __forceinline__ void gemm_tile64(const bf16_t* A, const bf16_t* Bt, int tm, int tn, const Epi& epi, char* smem, const float* ssq, int nparts) {
;     ...
;     f32x4 acc[4][4];
; #pragma unroll
;     for (int m = 0; m < 4; ++m)
; #pragma unroll
;         for (int n = 0; n < 4; ++n) acc[m][n] = (f32x4){0.f, 0.f, 0.f, 0.f};
;     if (nparts > 0 && tid < 128) {
;         float sq = 0.f;
;         for (int q = 0; q < nparts; ++q) sq += ssq[(size_t)q * T + (size_t)tm * 128 + tid];
;         sRs[tid] = rsqrtf(sq * (1.0f / 1024.0f) + EPS);
;     }
;     const int lrow = tid >> 3, lc8 = tid & 7;
;     const bf16_t* Ap = A + ((size_t)tm * 128 + lrow) * K + lc8 * 8;
;     const bf16_t* Bp = Bt + ((size_t)tn * 128 + lrow) * K + lc8 * 8;
;     struct Slab { u32x4 a[4], b[4]; };
;     auto gload = [&](int kt, Slab& sl) {
; #pragma unroll
;         for (int i = 0; i < 4; ++i) { sl.a[i] = *(const u32x4*)(Ap + (size_t)(32 * i) * K + kt * 64); sl.b[i] = *(const u32x4*)(Bp + (size_t)(32 * i) * K + kt * 64); }
;     };
;     auto sstore = [&](const Slab& sl) {
; #pragma unroll
;         for (int i = 0; i < 4; ++i) {
;             const int r = lrow + 32 * i;
;             *(u32x4*)(sA + r * 64 + ((lc8 ^ ((r >> 1) & 7)) * 8)) = sl.a[i];
;             const int rs = (r & 64) | (((r >> 2) & 3) << 4) | (((r >> 4) & 3) << 2) | (r & 3);
;             *(u32x4*)(sB + rs * 64 + ((lc8 ^ ((rs >> 1) & 7)) * 8)) = sl.b[i];
;         }
;     };
;     auto compute = [&]() {
; #pragma unroll
;         for (int ks = 0; ks < 2; ++ks) {
;             bf16x8 af[4], bfr[4];
; #pragma unroll
;             for (int m = 0; m < 4; ++m) { const int r = wr * 64 + m * 16 + fr; af[m] = *(const bf16x8*)(sA + r * 64 + (((ks * 4 + fq) ^ ((r >> 1) & 7)) * 8)); }
; #pragma unroll
;             for (int n = 0; n < 4; ++n) { const int r = wc * 64 + n * 16 + fr; bfr[n] = *(const bf16x8*)(sB + r * 64 + (((ks * 4 + fq) ^ ((r >> 1) & 7)) * 8)); }
; #pragma unroll
;             for (int m = 0; m < 4; ++m)
; #pragma unroll
;                 for (int n = 0; n < 4; ++n) acc[m][n] = __builtin_amdgcn_mfma_f32_16x16x32_bf16(bfr[n], af[m], acc[m][n], 0, 0, 0);
;         }
;     };
;     Slab s0;
;     gload(0, s0);
.LBB0_50:
	s_or_b64 exec, exec, s[22:23]
	s_and_b32 s14, s13, 63
	s_ashr_i32 s13, s13, 5
	s_and_b32 s13, s13, -8
	s_lshr_b32 s14, s14, 3
	v_readlane_b32 s36, v165, 42
	s_or_b32 s22, s14, s13
	v_ashrrev_i32_e32 v2, 3, v0
	s_lshl_b32 s13, s12, 18
	v_readlane_b32 s46, v165, 52
	v_ashrrev_i32_e32 v3, 31, v2
	v_readlane_b32 s47, v165, 53
	s_add_u32 s14, s46, s13
	s_addc_u32 s15, s47, 0
	v_lshlrev_b64 v[4:5], 11, v[2:3]
	s_ashr_i32 s23, s22, 31
	v_lshl_add_u64 v[6:7], s[14:15], 0, v[4:5]
	s_lshl_b64 s[14:15], s[22:23], 18
	s_add_u32 s14, s10, s14
	v_lshlrev_b32_e32 v3, 4, v0
	s_addc_u32 s15, s11, s15
	v_and_b32_e32 v112, 0x70, v3
	v_lshl_add_u64 v[4:5], s[14:15], 0, v[4:5]
	v_lshl_add_u64 v[66:67], v[4:5], 0, v[112:113]
	v_lshlrev_b32_e32 v4, 2, v2
	v_lshrrev_b32_e32 v5, 2, v2
	v_lshl_add_u64 v[64:65], v[6:7], 0, v[112:113]
	v_and_b32_e32 v4, 48, v4
	v_and_b32_e32 v5, 12, v5
	v_and_b32_e32 v6, 0x43, v2
	v_or3_b32 v6, v4, v6, v5
	v_lshrrev_b32_e32 v7, 1, v6
	v_lshrrev_b32_e32 v3, 1, v2
	v_xor_b32_e32 v7, v7, v0
	v_xor_b32_e32 v3, v3, v0
	v_lshlrev_b32_e32 v7, 4, v7
	v_lshlrev_b32_e32 v3, 4, v3
	v_and_b32_e32 v7, 0x70, v7
	v_and_b32_e32 v3, 0x70, v3
	v_lshl_or_b32 v101, v6, 7, v7
	v_add_u32_e32 v6, 32, v2
	v_lshl_or_b32 v102, v6, 7, v3
	v_and_b32_e32 v7, 64, v6
	v_lshrrev_b32_e32 v6, 2, v6
	v_and_b32_e32 v6, 12, v6
	v_and_or_b32 v4, v2, 3, v4
	v_or3_b32 v6, v6, v7, v4
	v_lshrrev_b32_e32 v7, 1, v6
	v_xor_b32_e32 v7, v7, v0
	v_lshlrev_b32_e32 v7, 4, v7
	v_and_b32_e32 v7, 0x70, v7
	v_lshl_or_b32 v100, v2, 7, v3
	v_lshl_or_b32 v103, v6, 7, v7
	v_add_u32_e32 v6, 64, v2
	v_add_u32_e32 v2, 0x60, v2
	v_lshl_or_b32 v104, v6, 7, v3
	v_lshl_or_b32 v106, v2, 7, v3
	v_and_b32_e32 v3, 64, v2
	v_lshrrev_b32_e32 v2, 2, v2
	v_and_b32_e32 v2, 12, v2
	v_or3_b32 v2, v2, v3, v4
	v_and_b32_e32 v6, 64, v6
	v_lshrrev_b32_e32 v3, 1, v2
	v_or3_b32 v5, v5, v6, v4
	v_xor_b32_e32 v3, v3, v0
	v_lshrrev_b32_e32 v6, 1, v5
	v_lshlrev_b32_e32 v3, 4, v3
	v_bfe_u32 v98, v0, 6, 1
	v_lshrrev_b32_e32 v1, 4, v0
	v_ashrrev_i32_e32 v97, 7, v0
	v_and_b32_e32 v96, 15, v0
	v_bfe_u32 v99, v0, 4, 2
	s_mov_b64 s[14:15], 0x10000
	v_xor_b32_e32 v6, v6, v0
	v_and_b32_e32 v3, 0x70, v3
	v_bfe_u32 v0, v0, 1, 3
	v_lshl_add_u64 v[68:69], v[64:65], 0, s[14:15]
	v_lshl_add_u64 v[70:71], v[66:67], 0, s[14:15]
	s_mov_b64 s[14:15], 0x30000
	v_lshlrev_b32_e32 v6, 4, v6
	v_lshl_or_b32 v107, v2, 7, v3
	v_bitop3_b32 v1, v1, v0, 3 bitop3:0x6c
	v_lshlrev_b32_e32 v2, 7, v96
	v_bitop3_b32 v0, v99, v0, 4 bitop3:0x36
	v_lshl_add_u64 v[72:73], v[64:65], 0, s[66:67]
	v_lshl_add_u64 v[74:75], v[66:67], 0, s[66:67]
	v_lshl_add_u64 v[76:77], v[64:65], 0, s[14:15]
	v_lshl_add_u64 v[78:79], v[66:67], 0, s[14:15]
	v_and_b32_e32 v6, 0x70, v6
	v_lshlrev_b32_e32 v1, 4, v1
	v_lshl_or_b32 v3, v97, 13, v2
	v_lshl_or_b32 v2, v98, 13, v2
	v_lshlrev_b32_e32 v0, 4, v0
	v_mov_b32_e32 v4, 0
	s_mov_b32 s13, 1
	v_lshl_or_b32 v105, v5, 7, v6
	v_or_b32_e32 v108, v1, v3
	v_or_b32_e32 v109, v1, v2
	v_or_b32_e32 v110, v0, v3
	v_or_b32_e32 v111, v0, v2
	s_waitcnt vmcnt(5)
	v_lshrrev_b32_e32 v135, 3, v130
	v_and_b32_e32 v141, 7, v130
	v_lshlrev_b32_e32 v135, 11, v135
	v_readfirstlane_b32 s98, v64
	v_readfirstlane_b32 s99, v65
	v_lshl_or_b32 v135, v141, 4, v135
	v_readfirstlane_b32 s20, v66
	v_readfirstlane_b32 s21, v67
	v_add_u32_e32 v136, 0x10000, v135
	v_add_u32_e32 v137, 0x20000, v135
	v_add_u32_e32 v138, 0x30000, v135
	v_mov_b32_e32 v5, v4
	v_mov_b32_e32 v6, v4
	v_mov_b32_e32 v7, v4
	v_mov_b32_e32 v8, v4
	v_mov_b32_e32 v9, v4
	v_mov_b32_e32 v10, v4
	v_mov_b32_e32 v11, v4
	v_mov_b32_e32 v16, v4
	v_mov_b32_e32 v17, v4
	v_mov_b32_e32 v18, v4
	v_mov_b32_e32 v19, v4
	v_mov_b32_e32 v0, v4
	v_mov_b32_e32 v1, v4
	v_mov_b32_e32 v2, v4
	v_mov_b32_e32 v3, v4
	v_mov_b32_e32 v12, v4
	v_mov_b32_e32 v13, v4
	v_mov_b32_e32 v14, v4
	v_mov_b32_e32 v15, v4
	v_mov_b32_e32 v20, v4
	v_mov_b32_e32 v21, v4
	v_mov_b32_e32 v22, v4
	v_mov_b32_e32 v23, v4
	v_mov_b32_e32 v24, v4
	v_mov_b32_e32 v25, v4
	v_mov_b32_e32 v26, v4
	v_mov_b32_e32 v27, v4
	v_mov_b32_e32 v28, v4
	v_mov_b32_e32 v29, v4
	v_mov_b32_e32 v30, v4
	v_mov_b32_e32 v31, v4
	v_mov_b32_e32 v32, v4
	v_mov_b32_e32 v33, v4
	v_mov_b32_e32 v34, v4
	v_mov_b32_e32 v35, v4
	v_mov_b32_e32 v36, v4
	v_mov_b32_e32 v37, v4
	v_mov_b32_e32 v38, v4
	v_mov_b32_e32 v39, v4
	v_mov_b32_e32 v40, v4
	v_mov_b32_e32 v41, v4
	v_mov_b32_e32 v42, v4
	v_mov_b32_e32 v43, v4
	v_mov_b32_e32 v44, v4
	v_mov_b32_e32 v45, v4
	v_mov_b32_e32 v46, v4
	v_mov_b32_e32 v47, v4
	v_mov_b32_e32 v48, v4
	v_mov_b32_e32 v49, v4
	v_mov_b32_e32 v50, v4
	v_mov_b32_e32 v51, v4
	v_mov_b32_e32 v52, v4
	v_mov_b32_e32 v53, v4
	v_mov_b32_e32 v54, v4
	v_mov_b32_e32 v55, v4
	v_mov_b32_e32 v56, v4
	v_mov_b32_e32 v57, v4
	v_mov_b32_e32 v58, v4
	v_mov_b32_e32 v59, v4
	v_mov_b32_e32 v60, v4
	v_mov_b32_e32 v61, v4
	v_mov_b32_e32 v62, v4
	v_mov_b32_e32 v63, v4
	v_readlane_b32 s37, v165, 43
	v_readlane_b32 s38, v165, 44
	v_readlane_b32 s39, v165, 45
	v_readlane_b32 s40, v165, 46
	v_readlane_b32 s41, v165, 47
	v_readlane_b32 s42, v165, 48
	v_readlane_b32 s43, v165, 49
	v_readlane_b32 s44, v165, 50
	v_readlane_b32 s45, v165, 51
	v_readlane_b32 s48, v165, 54
	v_readlane_b32 s49, v165, 55
	v_readlane_b32 s50, v165, 56
	v_readlane_b32 s51, v165, 57
	global_load_dwordx4 v[64:67], v135, s[98:99]
	global_load_dwordx4 v[68:71], v135, s[20:21]
	global_load_dwordx4 v[72:75], v136, s[98:99]
	global_load_dwordx4 v[76:79], v136, s[20:21]
	global_load_dwordx4 v[156:159], v137, s[98:99]
	global_load_dwordx4 v[160:163], v137, s[20:21]
	global_load_dwordx4 v[148:151], v138, s[98:99]
	global_load_dwordx4 v[152:155], v138, s[20:21]
	s_add_u32 s98, s98, 0x80
	s_addc_u32 s99, s99, 0
	s_add_u32 s20, s20, 0x80
	s_addc_u32 s21, s21, 0
; template <class Epi>
; __device__ __forceinline__ void gemm_tile64(const bf16_t* A, const bf16_t* Bt, int tm, int tn, const Epi& epi, char* smem, const float* ssq, int nparts) {
;     ...
;     auto gload = [&](int kt, Slab& sl) {
; #pragma unroll
;         for (int i = 0; i < 4; ++i) { sl.a[i] = *(const u32x4*)(Ap + (size_t)(32 * i) * K + kt * 64); sl.b[i] = *(const u32x4*)(Bp + (size_t)(32 * i) * K + kt * 64); }
;     };
;     auto sstore = [&](const Slab& sl) {
; #pragma unroll
;         for (int i = 0; i < 4; ++i) {
;             const int r = lrow + 32 * i;
;             *(u32x4*)(sA + r * 64 + ((lc8 ^ ((r >> 1) & 7)) * 8)) = sl.a[i];
;             const int rs = (r & 64) | (((r >> 2) & 3) << 4) | (((r >> 4) & 3) << 2) | (r & 3);
;             *(u32x4*)(sB + rs * 64 + ((lc8 ^ ((rs >> 1) & 7)) * 8)) = sl.b[i];
;         }
;     };
;     auto compute = [&]() {
; #pragma unroll
;         for (int ks = 0; ks < 2; ++ks) {
;             bf16x8 af[4], bfr[4];
; #pragma unroll
;             for (int m = 0; m < 4; ++m) { const int r = wr * 64 + m * 16 + fr; af[m] = *(const bf16x8*)(sA + r * 64 + (((ks * 4 + fq) ^ ((r >> 1) & 7)) * 8)); }
; #pragma unroll
;             for (int n = 0; n < 4; ++n) { const int r = wc * 64 + n * 16 + fr; bfr[n] = *(const bf16x8*)(sB + r * 64 + (((ks * 4 + fq) ^ ((r >> 1) & 7)) * 8)); }
; #pragma unroll
;             for (int m = 0; m < 4; ++m)
; #pragma unroll
;                 for (int n = 0; n < 4; ++n) acc[m][n] = __builtin_amdgcn_mfma_f32_16x16x32_bf16(bfr[n], af[m], acc[m][n], 0, 0, 0);
;         }
;     };
;     Slab s0;
;     gload(0, s0);
;     for (int kt = 0; kt < 16; ++kt) {
;         __syncthreads(); sstore(s0); __syncthreads();
;         gload(min(kt + 1, 15), s0);
;         compute();
;     }
.LBB0_51:
	s_waitcnt lgkmcnt(0)
	s_barrier
	s_waitcnt vmcnt(7)
	ds_write_b128 v100, v[64:67]
	s_waitcnt vmcnt(6)
	ds_write_b128 v101, v[68:71] offset:16384
	s_waitcnt vmcnt(5)
	ds_write_b128 v102, v[72:75]
	s_waitcnt vmcnt(4)
	ds_write_b128 v103, v[76:79] offset:16384
	s_waitcnt vmcnt(3)
	ds_write_b128 v104, v[156:159]
	s_waitcnt vmcnt(2)
	ds_write_b128 v105, v[160:163] offset:16384
	s_waitcnt vmcnt(1)
	ds_write_b128 v106, v[148:151]
	s_waitcnt vmcnt(0)
	ds_write_b128 v107, v[152:155] offset:16384
	s_add_i32 s13, s13, 1
	s_waitcnt lgkmcnt(0)
	s_barrier
	ds_read_b128 v[80:83], v109 offset:16384
	ds_read_b128 v[84:87], v109 offset:18432
	ds_read_b128 v[88:91], v108
	ds_read_b128 v[92:95], v108 offset:2048
	ds_read_b128 v[116:119], v109 offset:20480
	ds_read_b128 v[120:123], v109 offset:22528
	s_cmp_eq_u32 s13, 17
	s_cbranch_scc1 .Lgs_nopf
	global_load_dwordx4 v[64:67], v135, s[98:99]
	global_load_dwordx4 v[68:71], v135, s[20:21]
	global_load_dwordx4 v[72:75], v136, s[98:99]
	global_load_dwordx4 v[76:79], v136, s[20:21]
	global_load_dwordx4 v[156:159], v137, s[98:99]
	global_load_dwordx4 v[160:163], v137, s[20:21]
	global_load_dwordx4 v[148:151], v138, s[98:99]
	global_load_dwordx4 v[152:155], v138, s[20:21]
	s_add_u32 s98, s98, 0x80
	s_addc_u32 s99, s99, 0
	s_add_u32 s20, s20, 0x80
	s_addc_u32 s21, s21, 0
.Lgs_nopf:
	s_waitcnt lgkmcnt(3)
	v_mfma_f32_16x16x32_bf16 v[60:63], v[80:83], v[88:91], v[60:63]
	v_mfma_f32_16x16x32_bf16 v[56:59], v[84:87], v[88:91], v[56:59]
	s_waitcnt lgkmcnt(1)
	v_mfma_f32_16x16x32_bf16 v[52:55], v[116:119], v[88:91], v[52:55]
	s_waitcnt lgkmcnt(0)
	v_mfma_f32_16x16x32_bf16 v[48:51], v[120:123], v[88:91], v[48:51]
	v_mfma_f32_16x16x32_bf16 v[44:47], v[80:83], v[92:95], v[44:47]
	v_mfma_f32_16x16x32_bf16 v[40:43], v[84:87], v[92:95], v[40:43]
	v_mfma_f32_16x16x32_bf16 v[36:39], v[116:119], v[92:95], v[36:39]
	v_mfma_f32_16x16x32_bf16 v[32:35], v[120:123], v[92:95], v[32:35]
	ds_read_b128 v[88:91], v108 offset:4096
	ds_read_b128 v[92:95], v108 offset:6144
	s_waitcnt lgkmcnt(1)
	v_mfma_f32_16x16x32_bf16 v[28:31], v[80:83], v[88:91], v[28:31]
	v_mfma_f32_16x16x32_bf16 v[24:27], v[84:87], v[88:91], v[24:27]
	v_mfma_f32_16x16x32_bf16 v[20:23], v[116:119], v[88:91], v[20:23]
	v_mfma_f32_16x16x32_bf16 v[12:15], v[120:123], v[88:91], v[12:15]
	s_waitcnt lgkmcnt(0)
	v_mfma_f32_16x16x32_bf16 v[0:3], v[80:83], v[92:95], v[0:3]
	v_mfma_f32_16x16x32_bf16 v[16:19], v[84:87], v[92:95], v[16:19]
	ds_read_b128 v[80:83], v111 offset:16384
	ds_read_b128 v[84:87], v111 offset:18432
	v_mfma_f32_16x16x32_bf16 v[8:11], v[116:119], v[92:95], v[8:11]
	v_mfma_f32_16x16x32_bf16 v[4:7], v[120:123], v[92:95], v[4:7]
	ds_read_b128 v[88:91], v110
	ds_read_b128 v[92:95], v110 offset:2048
	ds_read_b128 v[116:119], v111 offset:20480
	ds_read_b128 v[120:123], v111 offset:22528
	s_waitcnt lgkmcnt(3)
	v_mfma_f32_16x16x32_bf16 v[60:63], v[80:83], v[88:91], v[60:63]
	v_mfma_f32_16x16x32_bf16 v[56:59], v[84:87], v[88:91], v[56:59]
	s_waitcnt lgkmcnt(1)
	v_mfma_f32_16x16x32_bf16 v[52:55], v[116:119], v[88:91], v[52:55]
	s_waitcnt lgkmcnt(0)
	v_mfma_f32_16x16x32_bf16 v[48:51], v[120:123], v[88:91], v[48:51]
	ds_read_b128 v[88:91], v110 offset:4096
	ds_read_b128 v[144:147], v110 offset:6144
	v_mfma_f32_16x16x32_bf16 v[44:47], v[80:83], v[92:95], v[44:47]
	v_mfma_f32_16x16x32_bf16 v[40:43], v[84:87], v[92:95], v[40:43]
	v_mfma_f32_16x16x32_bf16 v[36:39], v[116:119], v[92:95], v[36:39]
	v_mfma_f32_16x16x32_bf16 v[32:35], v[120:123], v[92:95], v[32:35]
	s_waitcnt lgkmcnt(1)
	v_mfma_f32_16x16x32_bf16 v[28:31], v[80:83], v[88:91], v[28:31]
	v_mfma_f32_16x16x32_bf16 v[24:27], v[84:87], v[88:91], v[24:27]
	v_mfma_f32_16x16x32_bf16 v[20:23], v[116:119], v[88:91], v[20:23]
	v_mfma_f32_16x16x32_bf16 v[12:15], v[120:123], v[88:91], v[12:15]
	s_waitcnt lgkmcnt(0)
	v_mfma_f32_16x16x32_bf16 v[0:3], v[80:83], v[144:147], v[0:3]
	v_mfma_f32_16x16x32_bf16 v[16:19], v[84:87], v[144:147], v[16:19]
	v_mfma_f32_16x16x32_bf16 v[8:11], v[116:119], v[144:147], v[8:11]
	v_mfma_f32_16x16x32_bf16 v[4:7], v[120:123], v[144:147], v[4:7]
	s_cmp_eq_u32 s13, 17
	s_cbranch_scc0 .LBB0_51
	s_mov_b32 s21, 0
	s_movk_i32 s20, 0x780
	s_mov_b32 s14, 15
	v_lshl_or_b32 v64, v97, 6, v96
	v_lshlrev_b32_e32 v67, 2, v64
	ds_read_b32 v66, v67 offset:32768
	v_or3_b32 v65, v98, s22, v99
	v_cmp_eq_u32_e32 vcc, 0, v65
	s_lshl_b32 s13, s12, 9
	v_ashrrev_i32_e32 v65, 31, v64
	s_and_saveexec_b64 s[24:25], vcc
	s_cbranch_execz .LBB0_54
	v_readlane_b32 s36, v165, 42
	v_readlane_b32 s40, v165, 46
	v_readlane_b32 s41, v165, 47
	s_add_u32 s14, s40, s13
	s_addc_u32 s15, s41, 0
	v_lshl_add_u64 v[68:69], v[64:65], 2, s[14:15]
	v_readlane_b32 s37, v165, 43
	v_readlane_b32 s38, v165, 44
	v_readlane_b32 s39, v165, 45
	v_readlane_b32 s42, v165, 48
	v_readlane_b32 s43, v165, 49
	v_readlane_b32 s44, v165, 50
	v_readlane_b32 s45, v165, 51
	v_readlane_b32 s46, v165, 52
	v_readlane_b32 s47, v165, 53
	v_readlane_b32 s48, v165, 54
	v_readlane_b32 s49, v165, 55
	v_readlane_b32 s50, v165, 56
	v_readlane_b32 s51, v165, 57
	s_waitcnt lgkmcnt(0)
	global_store_dword v[68:69], v66, off

; __device__ __forceinline__ bool gemm_ticket(unsigned* ctr, int nt, int& tm, int& tn, char* smem) {
;     ...
;     const int j = sT[0];
;     if (j >= 32 * nt) return false;
;     const int full = nt >> 3, rem = nt & 7;
;     int tn_g, tm_g, q;
;     if (j < full * 256) { tn_g = j >> 8; const int r = j & 255; tm_g = r >> 6; q = r & 63; }
;     else { const int r = j - full * 256; tn_g = full; tm_g = r / (8 * rem); q = r % (8 * rem); }
;     tm = ((tm_g * 8 + (q & 7)) * 8) + xcd; tn = tn_g * 8 + (q >> 3); return true;
; }
; template <class Epi>
; __device__ __forceinline__ void gemm_tile64(const bf16_t* A, const bf16_t* Bt, int tm, int tn, const Epi& epi, char* smem, const float* ssq, int nparts) {
;     constexpr int K = 1024;
;     bf16_t* sA = (bf16_t*)smem;
;     bf16_t* sB = sA + 8192;
;     float* sRs = (float*)(smem + 32768);
;     const int tid = get_tid(), lane = tid & 63, wid = tid >> 6, wr = wid >> 1, wc = wid & 1, fr = lane & 15, fq = lane >> 4;
;     f32x4 acc[4][4];
; #pragma unroll
;     for (int m = 0; m < 4; ++m)
; #pragma unroll
;         for (int n = 0; n < 4; ++n) acc[m][n] = (f32x4){0.f, 0.f, 0.f, 0.f};
;     if (nparts > 0 && tid < 128) {
;         float sq = 0.f;
;         for (int q = 0; q < nparts; ++q) sq += ssq[(size_t)q * T + (size_t)tm * 128 + tid];
;         sRs[tid] = rsqrtf(sq * (1.0f / 1024.0f) + EPS);
;     }
;     const int lrow = tid >> 3, lc8 = tid & 7;
;     const bf16_t* Ap = A + ((size_t)tm * 128 + lrow) * K + lc8 * 8;
;     const bf16_t* Bp = Bt + ((size_t)tn * 128 + lrow) * K + lc8 * 8;
;     struct Slab { u32x4 a[4], b[4]; };
;     auto gload = [&](int kt, Slab& sl) {
; #pragma unroll
;         for (int i = 0; i < 4; ++i) { sl.a[i] = *(const u32x4*)(Ap + (size_t)(32 * i) * K + kt * 64); sl.b[i] = *(const u32x4*)(Bp + (size_t)(32 * i) * K + kt * 64); }
;     };
;     auto sstore = [&](const Slab& sl) {
; #pragma unroll
;         for (int i = 0; i < 4; ++i) {
;             const int r = lrow + 32 * i;
;             *(u32x4*)(sA + r * 64 + ((lc8 ^ ((r >> 1) & 7)) * 8)) = sl.a[i];
;             const int rs = (r & 64) | (((r >> 2) & 3) << 4) | (((r >> 4) & 3) << 2) | (r & 3);
;             *(u32x4*)(sB + rs * 64 + ((lc8 ^ ((rs >> 1) & 7)) * 8)) = sl.b[i];
;         }
;     };
;     auto compute = [&]() {
; #pragma unroll
;         for (int ks = 0; ks < 2; ++ks) {
;             bf16x8 af[4], bfr[4];
; #pragma unroll
.LBB0_69:
	s_or_b64 exec, exec, s[0:1]
	s_waitcnt lgkmcnt(0)
	s_barrier
	ds_read_b32 v0, v113 offset:33280
	s_movk_i32 s0, 0xff
	s_waitcnt lgkmcnt(0)
	v_cmp_lt_i32_e32 vcc, s0, v0
	v_readfirstlane_b32 s13, v0
	s_mov_b64 s[0:1], -1
	s_cbranch_vccnz .LBB0_64
	s_lshl_b32 s1, s13, 3
	s_and_b32 s0, s13, 0xc0
	s_and_b32 s1, s1, 56
	s_or_b32 s0, s0, s1
	s_or_b32 s12, s0, s12
	s_ashr_i32 s0, s13, 5
	s_and_b32 s0, s0, -8
	s_bfe_u32 s1, s13, 0x30003
	v_mov_b32_e32 v6, v126
	s_or_b32 s0, s1, s0
	s_lshl_b32 s1, s12, 18
	v_ashrrev_i32_e32 v0, 3, v6
	v_readlane_b32 s14, v165, 8
	v_ashrrev_i32_e32 v1, 31, v0
	v_readlane_b32 s15, v165, 9
	s_add_u32 s14, s14, s1
	s_addc_u32 s15, s15, 0
	v_lshlrev_b64 v[2:3], 11, v[0:1]
	s_ashr_i32 s1, s0, 31
	v_lshl_add_u64 v[4:5], s[14:15], 0, v[2:3]
	s_lshl_b64 s[14:15], s[0:1], 18
	s_add_u32 s14, s10, s14
	v_lshlrev_b32_e32 v1, 4, v6
	s_addc_u32 s15, s11, s15
	v_and_b32_e32 v112, 0x70, v1
	v_lshl_add_u64 v[2:3], s[14:15], 0, v[2:3]
	v_lshl_add_u64 v[66:67], v[2:3], 0, v[112:113]
	v_lshlrev_b32_e32 v2, 2, v0
	v_lshrrev_b32_e32 v3, 2, v0
	v_lshl_add_u64 v[64:65], v[4:5], 0, v[112:113]
	v_and_b32_e32 v2, 48, v2
	v_and_b32_e32 v3, 12, v3
	v_and_b32_e32 v4, 0x43, v0
	v_or3_b32 v4, v2, v4, v3
	v_lshrrev_b32_e32 v5, 1, v4
	v_lshrrev_b32_e32 v1, 1, v0
	v_xor_b32_e32 v5, v5, v6
	v_xor_b32_e32 v1, v1, v6
	v_lshlrev_b32_e32 v5, 4, v5
	v_lshlrev_b32_e32 v1, 4, v1
	v_and_b32_e32 v5, 0x70, v5
	v_and_b32_e32 v1, 0x70, v1
	v_lshl_or_b32 v101, v4, 7, v5
	v_add_u32_e32 v4, 32, v0
	v_lshl_or_b32 v102, v4, 7, v1
	v_and_b32_e32 v5, 64, v4
	v_lshrrev_b32_e32 v4, 2, v4
	v_and_b32_e32 v4, 12, v4
	v_and_or_b32 v2, v0, 3, v2
	v_or3_b32 v4, v4, v5, v2
	v_lshrrev_b32_e32 v5, 1, v4
	v_xor_b32_e32 v5, v5, v6
	v_lshlrev_b32_e32 v5, 4, v5
	v_and_b32_e32 v5, 0x70, v5
	v_lshl_or_b32 v100, v0, 7, v1
	v_lshl_or_b32 v103, v4, 7, v5
	v_add_u32_e32 v4, 64, v0
	v_add_u32_e32 v0, 0x60, v0
	v_lshl_or_b32 v104, v4, 7, v1
	v_lshl_or_b32 v106, v0, 7, v1
	v_and_b32_e32 v1, 64, v0
	v_lshrrev_b32_e32 v0, 2, v0
	v_and_b32_e32 v0, 12, v0
	v_or3_b32 v0, v0, v1, v2
	v_and_b32_e32 v4, 64, v4
	v_lshrrev_b32_e32 v1, 1, v0
	v_or3_b32 v3, v3, v4, v2
	v_xor_b32_e32 v1, v1, v6
	v_lshrrev_b32_e32 v4, 1, v3
	v_lshlrev_b32_e32 v1, 4, v1
	v_xor_b32_e32 v4, v4, v6
	v_and_b32_e32 v1, 0x70, v1
	v_lshrrev_b32_e32 v7, 4, v6
	v_and_b32_e32 v98, 15, v6
	v_bfe_u32 v97, v6, 4, 2
	v_lshlrev_b32_e32 v4, 4, v4
	v_lshl_or_b32 v107, v0, 7, v1
	v_bfe_u32 v0, v6, 1, 3
	v_bfe_u32 v96, v6, 6, 1
	v_ashrrev_i32_e32 v99, 7, v6
	s_mov_b64 s[14:15], 0x10000
	v_and_b32_e32 v4, 0x70, v4
	v_bitop3_b32 v1, v7, v0, 3 bitop3:0x6c
	v_lshlrev_b32_e32 v2, 7, v98
	v_bitop3_b32 v0, v97, v0, 4 bitop3:0x36
	v_lshl_add_u64 v[68:69], v[64:65], 0, s[14:15]
	v_lshl_add_u64 v[70:71], v[66:67], 0, s[14:15]
	s_mov_b64 s[14:15], 0x30000
	v_lshl_or_b32 v105, v3, 7, v4
	v_lshl_or_b32 v3, v99, 13, v2
	v_lshl_or_b32 v2, v96, 13, v2
	v_lshlrev_b32_e32 v0, 4, v0
	v_lshl_add_u64 v[72:73], v[64:65], 0, s[66:67]
	v_lshl_add_u64 v[74:75], v[66:67], 0, s[66:67]
	v_lshl_add_u64 v[76:77], v[64:65], 0, s[14:15]
	v_lshl_add_u64 v[78:79], v[66:67], 0, s[14:15]
	v_lshlrev_b32_e32 v1, 4, v1
	v_or_b32_e32 v110, v0, v3
	v_or_b32_e32 v111, v0, v2
	v_mov_b32_e32 v0, 0
	s_mov_b32 s1, 1
	v_or_b32_e32 v108, v1, v3
	v_or_b32_e32 v109, v1, v2
	s_waitcnt vmcnt(5)
	v_lshrrev_b32_e32 v135, 3, v130
	v_and_b32_e32 v141, 7, v130
	v_lshlrev_b32_e32 v135, 11, v135
	v_readfirstlane_b32 s98, v64
	v_readfirstlane_b32 s99, v65
	v_lshl_or_b32 v135, v141, 4, v135
	v_readfirstlane_b32 s20, v66
	v_readfirstlane_b32 s21, v67
	v_add_u32_e32 v136, 0x10000, v135
	v_add_u32_e32 v137, 0x20000, v135
	v_add_u32_e32 v138, 0x30000, v135
	v_mov_b32_e32 v1, v0
	v_mov_b32_e32 v2, v0
	v_mov_b32_e32 v3, v0
	v_mov_b32_e32 v8, v0
	v_mov_b32_e32 v9, v0
	v_mov_b32_e32 v10, v0
	v_mov_b32_e32 v11, v0
	v_mov_b32_e32 v12, v0
	v_mov_b32_e32 v13, v0
	v_mov_b32_e32 v14, v0
	v_mov_b32_e32 v15, v0
	v_mov_b32_e32 v4, v0
	v_mov_b32_e32 v5, v0
	v_mov_b32_e32 v6, v0
	v_mov_b32_e32 v7, v0
	v_mov_b32_e32 v16, v0
	v_mov_b32_e32 v17, v0
	v_mov_b32_e32 v18, v0
	v_mov_b32_e32 v19, v0
	v_mov_b32_e32 v20, v0
	v_mov_b32_e32 v21, v0
	v_mov_b32_e32 v22, v0
	v_mov_b32_e32 v23, v0
	v_mov_b32_e32 v24, v0
	v_mov_b32_e32 v25, v0
	v_mov_b32_e32 v26, v0
	v_mov_b32_e32 v27, v0
	v_mov_b32_e32 v28, v0
	v_mov_b32_e32 v29, v0
	v_mov_b32_e32 v30, v0
	v_mov_b32_e32 v31, v0
	v_mov_b32_e32 v32, v0
	v_mov_b32_e32 v33, v0
	v_mov_b32_e32 v34, v0
	v_mov_b32_e32 v35, v0
	v_mov_b32_e32 v36, v0
	v_mov_b32_e32 v37, v0
	v_mov_b32_e32 v38, v0
	v_mov_b32_e32 v39, v0
	v_mov_b32_e32 v40, v0
	v_mov_b32_e32 v41, v0
	v_mov_b32_e32 v42, v0
	v_mov_b32_e32 v43, v0
	v_mov_b32_e32 v44, v0
	v_mov_b32_e32 v45, v0
	v_mov_b32_e32 v46, v0
	v_mov_b32_e32 v47, v0
	v_mov_b32_e32 v48, v0
	v_mov_b32_e32 v49, v0
	v_mov_b32_e32 v50, v0
	v_mov_b32_e32 v51, v0
	v_mov_b32_e32 v52, v0
	v_mov_b32_e32 v53, v0
	v_mov_b32_e32 v54, v0
	v_mov_b32_e32 v55, v0
	v_mov_b32_e32 v56, v0
	v_mov_b32_e32 v57, v0
	v_mov_b32_e32 v58, v0
	v_mov_b32_e32 v59, v0
	v_mov_b32_e32 v60, v0
	v_mov_b32_e32 v61, v0
	v_mov_b32_e32 v62, v0
	v_mov_b32_e32 v63, v0
	global_load_dwordx4 v[64:67], v135, s[98:99]
	global_load_dwordx4 v[68:71], v135, s[20:21]
	global_load_dwordx4 v[72:75], v136, s[98:99]
	global_load_dwordx4 v[76:79], v136, s[20:21]
	global_load_dwordx4 v[156:159], v137, s[98:99]
	global_load_dwordx4 v[160:163], v137, s[20:21]
	global_load_dwordx4 v[148:151], v138, s[98:99]
	global_load_dwordx4 v[152:155], v138, s[20:21]
	s_add_u32 s98, s98, 0x80
	s_addc_u32 s99, s99, 0
	s_add_u32 s20, s20, 0x80
	s_addc_u32 s21, s21, 0
; template <class Epi>
; __device__ __forceinline__ void gemm_tile64(const bf16_t* A, const bf16_t* Bt, int tm, int tn, const Epi& epi, char* smem, const float* ssq, int nparts) {
;     ...
;         for (int i = 0; i < 4; ++i) { sl.a[i] = *(const u32x4*)(Ap + (size_t)(32 * i) * K + kt * 64); sl.b[i] = *(const u32x4*)(Bp + (size_t)(32 * i) * K + kt * 64); }
;     };
;     auto sstore = [&](const Slab& sl) {
; #pragma unroll
;         for (int i = 0; i < 4; ++i) {
;             const int r = lrow + 32 * i;
;             *(u32x4*)(sA + r * 64 + ((lc8 ^ ((r >> 1) & 7)) * 8)) = sl.a[i];
;             const int rs = (r & 64) | (((r >> 2) & 3) << 4) | (((r >> 4) & 3) << 2) | (r & 3);
;             *(u32x4*)(sB + rs * 64 + ((lc8 ^ ((rs >> 1) & 7)) * 8)) = sl.b[i];
;         }
;     };
;     auto compute = [&]() {
; #pragma unroll
;         for (int ks = 0; ks < 2; ++ks) {
;             bf16x8 af[4], bfr[4];
; #pragma unroll
;             for (int m = 0; m < 4; ++m) { const int r = wr * 64 + m * 16 + fr; af[m] = *(const bf16x8*)(sA + r * 64 + (((ks * 4 + fq) ^ ((r >> 1) & 7)) * 8)); }
; #pragma unroll
;             for (int n = 0; n < 4; ++n) { const int r = wc * 64 + n * 16 + fr; bfr[n] = *(const bf16x8*)(sB + r * 64 + (((ks * 4 + fq) ^ ((r >> 1) & 7)) * 8)); }
; #pragma unroll
;             for (int m = 0; m < 4; ++m)
; #pragma unroll
;                 for (int n = 0; n < 4; ++n) acc[m][n] = __builtin_amdgcn_mfma_f32_16x16x32_bf16(bfr[n], af[m], acc[m][n], 0, 0, 0);
;         }
;     };
;     Slab s0;
;     gload(0, s0);
;     for (int kt = 0; kt < 16; ++kt) {
;         __syncthreads(); sstore(s0); __syncthreads();
;         gload(min(kt + 1, 15), s0);
.LBB0_71:
	s_waitcnt lgkmcnt(0)
	s_barrier
	s_waitcnt vmcnt(7)
	ds_write_b128 v100, v[64:67]
	s_waitcnt vmcnt(6)
	ds_write_b128 v101, v[68:71] offset:16384
	s_waitcnt vmcnt(5)
	ds_write_b128 v102, v[72:75]
	s_waitcnt vmcnt(4)
	ds_write_b128 v103, v[76:79] offset:16384
	s_waitcnt vmcnt(3)
	ds_write_b128 v104, v[156:159]
	s_waitcnt vmcnt(2)
	ds_write_b128 v105, v[160:163] offset:16384
	s_waitcnt vmcnt(1)
	ds_write_b128 v106, v[148:151]
	s_waitcnt vmcnt(0)
	ds_write_b128 v107, v[152:155] offset:16384
	s_add_i32 s1, s1, 1
	s_waitcnt lgkmcnt(0)
	s_barrier
	ds_read_b128 v[80:83], v109 offset:16384
	ds_read_b128 v[84:87], v109 offset:18432
	ds_read_b128 v[88:91], v108
	ds_read_b128 v[92:95], v108 offset:2048
	ds_read_b128 v[116:119], v109 offset:20480
	ds_read_b128 v[120:123], v109 offset:22528
	s_cmp_eq_u32 s1, 17
	s_cbranch_scc1 .Lgo_nopf
	global_load_dwordx4 v[64:67], v135, s[98:99]
	global_load_dwordx4 v[68:71], v135, s[20:21]
	global_load_dwordx4 v[72:75], v136, s[98:99]
	global_load_dwordx4 v[76:79], v136, s[20:21]
	global_load_dwordx4 v[156:159], v137, s[98:99]
	global_load_dwordx4 v[160:163], v137, s[20:21]
	global_load_dwordx4 v[148:151], v138, s[98:99]
	global_load_dwordx4 v[152:155], v138, s[20:21]
	s_add_u32 s98, s98, 0x80
	s_addc_u32 s99, s99, 0
	s_add_u32 s20, s20, 0x80
	s_addc_u32 s21, s21, 0
; __device__ __forceinline__ unsigned pk_bf16(float lo, float hi) { unsigned r; asm("v_cvt_pk_bf16_f32 %0, %1, %2" : "=v"(r) : "v"(lo), "v"(hi)); return r; }
; template <class Epi>
; __device__ __forceinline__ void gemm_tile64(const bf16_t* A, const bf16_t* Bt, int tm, int tn, const Epi& epi, char* smem, const float* ssq, int nparts) {
;     ...
;             for (int m = 0; m < 4; ++m) { const int r = wr * 64 + m * 16 + fr; af[m] = *(const bf16x8*)(sA + r * 64 + (((ks * 4 + fq) ^ ((r >> 1) & 7)) * 8)); }
; #pragma unroll
;             for (int n = 0; n < 4; ++n) { const int r = wc * 64 + n * 16 + fr; bfr[n] = *(const bf16x8*)(sB + r * 64 + (((ks * 4 + fq) ^ ((r >> 1) & 7)) * 8)); }
; #pragma unroll
;             for (int m = 0; m < 4; ++m)
; #pragma unroll
;                 for (int n = 0; n < 4; ++n) acc[m][n] = __builtin_amdgcn_mfma_f32_16x16x32_bf16(bfr[n], af[m], acc[m][n], 0, 0, 0);
;         }
;     };
;     Slab s0;
;     gload(0, s0);
;     for (int kt = 0; kt < 16; ++kt) {
;         __syncthreads(); sstore(s0); __syncthreads();
;         gload(min(kt + 1, 15), s0);
;         compute();
;     __device__ __forceinline__ void operator()(const f32x4 (&acc)[4][4], int tm, int tn, int wr, int wc, int fr, int fq, const float*) const {
;         const int col0 = tn * 128 + wc * 64 + fq * 16;
; #pragma unroll
;         for (int m = 0; m < 4; ++m) {
;             const size_t row = (size_t)tm * 128 + wr * 64 + m * 16 + fr;
;             f32x4 o[4]; float sq = 0.f;
; #pragma unroll
;             for (int n = 0; n < 4; ++n) {
;                 o[n] = *(const f32x4*)(xin + row * 1024 + col0 + n * 4) + acc[m][n];
;                 *(f32x4*)(xout + row * 1024 + col0 + n * 4) = o[n];
;                 sq += o[n][0] * o[n][0] + o[n][1] * o[n][1] + o[n][2] * o[n][2] + o[n][3] * o[n][3];
;             }
;             u32x4 w0, w1;
;             w0.x = pk_bf16(o[0][0], o[0][1]); w0.y = pk_bf16(o[0][2], o[0][3]); w0.z = pk_bf16(o[1][0], o[1][1]); w0.w = pk_bf16(o[1][2], o[1][3]);
;             w1.x = pk_bf16(o[2][0], o[2][1]); w1.y = pk_bf16(o[2][2], o[2][3]); w1.z = pk_bf16(o[3][0], o[3][1]); w1.w = pk_bf16(o[3][2], o[3][3]);
;             *(u32x4*)(xb + row * 1024 + col0) = w0; *(u32x4*)(xb + row * 1024 + col0 + 8) = w1;
;             sq += __shfl_xor(sq, 16); sq += __shfl_xor(sq, 32);
;             if (fq == 0) ssq[(size_t)(tn * 2 + wc) * T + row] = sq;
.Lgo_nopf:
	s_waitcnt lgkmcnt(3)
	v_mfma_f32_16x16x32_bf16 v[60:63], v[80:83], v[88:91], v[60:63]
	v_mfma_f32_16x16x32_bf16 v[56:59], v[84:87], v[88:91], v[56:59]
	s_waitcnt lgkmcnt(1)
	v_mfma_f32_16x16x32_bf16 v[52:55], v[116:119], v[88:91], v[52:55]
	s_waitcnt lgkmcnt(0)
	v_mfma_f32_16x16x32_bf16 v[48:51], v[120:123], v[88:91], v[48:51]
	v_mfma_f32_16x16x32_bf16 v[44:47], v[80:83], v[92:95], v[44:47]
	v_mfma_f32_16x16x32_bf16 v[40:43], v[84:87], v[92:95], v[40:43]
	v_mfma_f32_16x16x32_bf16 v[36:39], v[116:119], v[92:95], v[36:39]
	v_mfma_f32_16x16x32_bf16 v[32:35], v[120:123], v[92:95], v[32:35]
	ds_read_b128 v[88:91], v108 offset:4096
	ds_read_b128 v[92:95], v108 offset:6144
	s_waitcnt lgkmcnt(1)
	v_mfma_f32_16x16x32_bf16 v[28:31], v[80:83], v[88:91], v[28:31]
	v_mfma_f32_16x16x32_bf16 v[24:27], v[84:87], v[88:91], v[24:27]
	v_mfma_f32_16x16x32_bf16 v[20:23], v[116:119], v[88:91], v[20:23]
	v_mfma_f32_16x16x32_bf16 v[16:19], v[120:123], v[88:91], v[16:19]
	s_waitcnt lgkmcnt(0)
	v_mfma_f32_16x16x32_bf16 v[4:7], v[80:83], v[92:95], v[4:7]
	v_mfma_f32_16x16x32_bf16 v[12:15], v[84:87], v[92:95], v[12:15]
	ds_read_b128 v[80:83], v111 offset:16384
	ds_read_b128 v[84:87], v111 offset:18432
	v_mfma_f32_16x16x32_bf16 v[8:11], v[116:119], v[92:95], v[8:11]
	v_mfma_f32_16x16x32_bf16 v[0:3], v[120:123], v[92:95], v[0:3]
	ds_read_b128 v[88:91], v110
	ds_read_b128 v[92:95], v110 offset:2048
	ds_read_b128 v[116:119], v111 offset:20480
	ds_read_b128 v[120:123], v111 offset:22528
	s_waitcnt lgkmcnt(3)
	v_mfma_f32_16x16x32_bf16 v[60:63], v[80:83], v[88:91], v[60:63]
	v_mfma_f32_16x16x32_bf16 v[56:59], v[84:87], v[88:91], v[56:59]
	s_waitcnt lgkmcnt(1)
	v_mfma_f32_16x16x32_bf16 v[52:55], v[116:119], v[88:91], v[52:55]
	s_waitcnt lgkmcnt(0)
	v_mfma_f32_16x16x32_bf16 v[48:51], v[120:123], v[88:91], v[48:51]
	ds_read_b128 v[88:91], v110 offset:4096
	ds_read_b128 v[144:147], v110 offset:6144
	v_mfma_f32_16x16x32_bf16 v[44:47], v[80:83], v[92:95], v[44:47]
	v_mfma_f32_16x16x32_bf16 v[40:43], v[84:87], v[92:95], v[40:43]
	v_mfma_f32_16x16x32_bf16 v[36:39], v[116:119], v[92:95], v[36:39]
	v_mfma_f32_16x16x32_bf16 v[32:35], v[120:123], v[92:95], v[32:35]
	s_waitcnt lgkmcnt(1)
	v_mfma_f32_16x16x32_bf16 v[28:31], v[80:83], v[88:91], v[28:31]
	v_mfma_f32_16x16x32_bf16 v[24:27], v[84:87], v[88:91], v[24:27]
	v_mfma_f32_16x16x32_bf16 v[20:23], v[116:119], v[88:91], v[20:23]
	v_mfma_f32_16x16x32_bf16 v[16:19], v[120:123], v[88:91], v[16:19]
	s_waitcnt lgkmcnt(0)
	v_mfma_f32_16x16x32_bf16 v[4:7], v[80:83], v[144:147], v[4:7]
	v_mfma_f32_16x16x32_bf16 v[12:15], v[84:87], v[144:147], v[12:15]
	v_mfma_f32_16x16x32_bf16 v[8:11], v[116:119], v[144:147], v[8:11]
	v_mfma_f32_16x16x32_bf16 v[0:3], v[120:123], v[144:147], v[0:3]
	s_cmp_eq_u32 s1, 17
	s_cbranch_scc0 .LBB0_71
	s_mov_b32 s21, 0
	s_movk_i32 s20, 0x780
	s_mov_b32 s13, 15
	v_lshlrev_b32_e32 v66, 6, v99
	s_lshl_b32 s20, s12, 7
	v_ashrrev_i32_e32 v67, 31, v66
	s_lshl_b32 s1, s0, 7
	v_lshlrev_b32_e32 v64, 6, v96
	v_lshlrev_b32_e32 v65, 4, v97
	v_lshl_add_u64 v[66:67], s[20:21], 0, v[66:67]
	v_or3_b32 v64, v64, s1, v65
	v_or_b32_e32 v66, v66, v98
	v_lshl_or_b32 v68, s0, 1, v96
	v_ashrrev_i32_e32 v65, 31, v64
	v_ashrrev_i32_e32 v69, 31, v68
	v_lshlrev_b64 v[76:77], 12, v[66:67]
	v_lshlrev_b64 v[70:71], 17, v[68:69]
	v_lshl_add_u64 v[72:73], s[22:23], 0, v[76:77]
	v_lshlrev_b64 v[68:69], 2, v[64:65]
	v_lshl_add_u64 v[78:79], v[72:73], 0, v[68:69]
	global_load_dwordx4 v[72:75], v[78:79], off
	v_readlane_b32 s36, v165, 42
	v_readlane_b32 s46, v165, 52
	v_readlane_b32 s47, v165, 53
	v_cmp_lt_i32_e64 s[0:1], v134, v132
	v_readlane_b32 s50, v165, 56
	v_readlane_b32 s51, v165, 57
	v_cmp_eq_u32_e32 vcc, 0, v97
	v_readlane_b32 s37, v165, 43
	v_readlane_b32 s38, v165, 44
	v_readlane_b32 s39, v165, 45
	v_readlane_b32 s40, v165, 46
	v_readlane_b32 s41, v165, 47
	v_readlane_b32 s42, v165, 48
	v_readlane_b32 s43, v165, 49
	v_readlane_b32 s44, v165, 50
	v_readlane_b32 s45, v165, 51
	v_readlane_b32 s48, v165, 54
	v_readlane_b32 s49, v165, 55
	s_waitcnt vmcnt(0)
	v_pk_add_f32 v[60:61], v[60:61], v[72:73]
	v_lshl_add_u64 v[72:73], s[82:83], 0, v[76:77]
	v_pk_add_f32 v[62:63], v[62:63], v[74:75]
	v_lshl_add_u64 v[76:77], v[72:73], 0, v[68:69]
	global_store_dwordx4 v[76:77], v[60:63], off
	global_load_dwordx4 v[72:75], v[78:79], off offset:16
	v_mul_f32_e32 v80, v61, v61
	v_fmac_f32_e32 v80, v60, v60
	v_fmac_f32_e32 v80, v62, v62
	v_fmac_f32_e32 v80, v63, v63
	v_cvt_pk_bf16_f32 v60, v60, v61
	v_cvt_pk_bf16_f32 v61, v62, v63
	s_waitcnt vmcnt(0)
	v_pk_add_f32 v[56:57], v[56:57], v[72:73]
	s_nop 0
	v_mul_f32_e32 v72, v57, v57
	v_pk_add_f32 v[58:59], v[58:59], v[74:75]
	v_fmac_f32_e32 v72, v56, v56
	v_fmac_f32_e32 v72, v58, v58
	global_store_dwordx4 v[76:77], v[56:59], off offset:16
	v_fmac_f32_e32 v72, v59, v59
	v_add_f32_e32 v80, v80, v72
	global_load_dwordx4 v[72:75], v[78:79], off offset:32
	v_cvt_pk_bf16_f32 v62, v56, v57
	v_cvt_pk_bf16_f32 v63, v58, v59
	s_waitcnt vmcnt(0)
	v_pk_add_f32 v[52:53], v[52:53], v[72:73]
	s_nop 0
	v_mul_f32_e32 v72, v53, v53
	v_pk_add_f32 v[54:55], v[54:55], v[74:75]
	v_fmac_f32_e32 v72, v52, v52
	v_fmac_f32_e32 v72, v54, v54
	global_store_dwordx4 v[76:77], v[52:55], off offset:32
	v_fmac_f32_e32 v72, v55, v55
	v_add_f32_e32 v80, v80, v72
	global_load_dwordx4 v[72:75], v[78:79], off offset:48
	v_cvt_pk_bf16_f32 v52, v52, v53
	v_cvt_pk_bf16_f32 v53, v54, v55
	s_waitcnt vmcnt(0)
	v_pk_add_f32 v[48:49], v[48:49], v[72:73]
	v_pk_add_f32 v[50:51], v[50:51], v[74:75]
	v_mul_f32_e32 v72, v49, v49
	global_store_dwordx4 v[76:77], v[48:51], off offset:48
	v_fmac_f32_e32 v72, v48, v48
	v_cvt_pk_bf16_f32 v54, v48, v49
	v_fmac_f32_e32 v72, v50, v50
	v_lshlrev_b64 v[48:49], 11, v[66:67]
	v_lshl_add_u64 v[48:49], s[46:47], 0, v[48:49]
	v_lshl_add_u64 v[48:49], v[64:65], 1, v[48:49]
	v_fmac_f32_e32 v72, v51, v51
	v_cvt_pk_bf16_f32 v55, v50, v51
	global_store_dwordx4 v[48:49], v[60:63], off
	global_store_dwordx4 v[48:49], v[52:55], off offset:16
	v_cndmask_b32_e64 v48, v130, v134, s[0:1]
	v_add_f32_e32 v72, v80, v72
	v_lshlrev_b32_e32 v50, 2, v48
	ds_bpermute_b32 v48, v50, v72
	v_cmp_lt_i32_e64 s[0:1], v133, v132
	s_waitcnt lgkmcnt(0)
	v_add_f32_e32 v52, v72, v48
	v_cndmask_b32_e64 v48, v130, v133, s[0:1]
	v_lshlrev_b32_e32 v51, 2, v48
	ds_bpermute_b32 v53, v51, v52
	v_lshl_add_u64 v[48:49], s[50:51], 0, v[70:71]
	v_lshl_add_u64 v[48:49], v[66:67], 2, v[48:49]
	s_and_saveexec_b64 s[0:1], vcc
	s_cbranch_execz .LBB0_74
	s_waitcnt lgkmcnt(0)
	v_add_f32_e32 v52, v52, v53
	global_store_dword v[48:49], v52, off

; template <class Epi>
; __device__ __forceinline__ void gemm_tile64(const bf16_t* A, const bf16_t* Bt, int tm, int tn, const Epi& epi, char* smem, const float* ssq, int nparts) {
;     ...
;     f32x4 acc[4][4];
; #pragma unroll
;     for (int m = 0; m < 4; ++m)
; #pragma unroll
;         for (int n = 0; n < 4; ++n) acc[m][n] = (f32x4){0.f, 0.f, 0.f, 0.f};
;     if (nparts > 0 && tid < 128) {
;         float sq = 0.f;
;         for (int q = 0; q < nparts; ++q) sq += ssq[(size_t)q * T + (size_t)tm * 128 + tid];
;         sRs[tid] = rsqrtf(sq * (1.0f / 1024.0f) + EPS);
;     }
;     const int lrow = tid >> 3, lc8 = tid & 7;
;     const bf16_t* Ap = A + ((size_t)tm * 128 + lrow) * K + lc8 * 8;
;     const bf16_t* Bp = Bt + ((size_t)tn * 128 + lrow) * K + lc8 * 8;
;     struct Slab { u32x4 a[4], b[4]; };
;     auto gload = [&](int kt, Slab& sl) {
; #pragma unroll
;         for (int i = 0; i < 4; ++i) { sl.a[i] = *(const u32x4*)(Ap + (size_t)(32 * i) * K + kt * 64); sl.b[i] = *(const u32x4*)(Bp + (size_t)(32 * i) * K + kt * 64); }
;     };
;     auto sstore = [&](const Slab& sl) {
; #pragma unroll
;         for (int i = 0; i < 4; ++i) {
;             const int r = lrow + 32 * i;
;             *(u32x4*)(sA + r * 64 + ((lc8 ^ ((r >> 1) & 7)) * 8)) = sl.a[i];
;             const int rs = (r & 64) | (((r >> 2) & 3) << 4) | (((r >> 4) & 3) << 2) | (r & 3);
;             *(u32x4*)(sB + rs * 64 + ((lc8 ^ ((rs >> 1) & 7)) * 8)) = sl.b[i];
;         }
;     };
;     auto compute = [&]() {
; #pragma unroll
;         for (int ks = 0; ks < 2; ++ks) {
;             bf16x8 af[4], bfr[4];
; #pragma unroll
;             for (int m = 0; m < 4; ++m) { const int r = wr * 64 + m * 16 + fr; af[m] = *(const bf16x8*)(sA + r * 64 + (((ks * 4 + fq) ^ ((r >> 1) & 7)) * 8)); }
; #pragma unroll
;             for (int n = 0; n < 4; ++n) { const int r = wc * 64 + n * 16 + fr; bfr[n] = *(const bf16x8*)(sB + r * 64 + (((ks * 4 + fq) ^ ((r >> 1) & 7)) * 8)); }
; #pragma unroll
;             for (int m = 0; m < 4; ++m)
; #pragma unroll
;                 for (int n = 0; n < 4; ++n) acc[m][n] = __builtin_amdgcn_mfma_f32_16x16x32_bf16(bfr[n], af[m], acc[m][n], 0, 0, 0);
;         }
;     };
;     Slab s0;
;     gload(0, s0);
.LBB0_375:
	s_or_b64 exec, exec, s[0:1]
	v_readlane_b32 s48, v165, 42
	v_ashrrev_i32_e32 v2, 3, v0
	s_lshl_b64 s[0:1], s[46:47], 18
	v_readlane_b32 s58, v165, 52
	v_ashrrev_i32_e32 v3, 31, v2
	v_readlane_b32 s59, v165, 53
	s_add_u32 s0, s58, s0
	s_addc_u32 s1, s59, s1
	v_lshlrev_b64 v[4:5], 11, v[2:3]
	s_ashr_i32 s23, s22, 31
	v_lshl_add_u64 v[6:7], s[0:1], 0, v[4:5]
	s_lshl_b64 s[0:1], s[22:23], 18
	s_add_u32 s0, s10, s0
	v_lshlrev_b32_e32 v3, 4, v0
	s_addc_u32 s1, s11, s1
	v_and_b32_e32 v112, 0x70, v3
	v_lshl_add_u64 v[4:5], s[0:1], 0, v[4:5]
	v_lshl_add_u64 v[66:67], v[4:5], 0, v[112:113]
	v_lshlrev_b32_e32 v4, 2, v2
	v_lshrrev_b32_e32 v5, 2, v2
	v_lshl_add_u64 v[64:65], v[6:7], 0, v[112:113]
	v_and_b32_e32 v4, 48, v4
	v_and_b32_e32 v5, 12, v5
	v_and_b32_e32 v6, 0x43, v2
	v_or3_b32 v6, v4, v6, v5
	v_lshrrev_b32_e32 v7, 1, v6
	v_lshrrev_b32_e32 v3, 1, v2
	v_xor_b32_e32 v7, v7, v0
	v_xor_b32_e32 v3, v3, v0
	v_lshlrev_b32_e32 v7, 4, v7
	v_lshlrev_b32_e32 v3, 4, v3
	v_and_b32_e32 v7, 0x70, v7
	v_and_b32_e32 v3, 0x70, v3
	v_lshl_or_b32 v101, v6, 7, v7
	v_add_u32_e32 v6, 32, v2
	v_lshl_or_b32 v102, v6, 7, v3
	v_and_b32_e32 v7, 64, v6
	v_lshrrev_b32_e32 v6, 2, v6
	v_and_b32_e32 v6, 12, v6
	v_and_or_b32 v4, v2, 3, v4
	v_or3_b32 v6, v6, v7, v4
	v_lshrrev_b32_e32 v7, 1, v6
	v_xor_b32_e32 v7, v7, v0
	v_lshlrev_b32_e32 v7, 4, v7
	v_and_b32_e32 v7, 0x70, v7
	v_lshl_or_b32 v100, v2, 7, v3
	v_lshl_or_b32 v103, v6, 7, v7
	v_add_u32_e32 v6, 64, v2
	v_add_u32_e32 v2, 0x60, v2
	v_lshl_or_b32 v104, v6, 7, v3
	v_lshl_or_b32 v106, v2, 7, v3
	v_and_b32_e32 v3, 64, v2
	v_lshrrev_b32_e32 v2, 2, v2
	v_and_b32_e32 v2, 12, v2
	v_or3_b32 v2, v2, v3, v4
	v_and_b32_e32 v6, 64, v6
	v_lshrrev_b32_e32 v3, 1, v2
	v_or3_b32 v5, v5, v6, v4
	v_xor_b32_e32 v3, v3, v0
	v_lshrrev_b32_e32 v6, 1, v5
	v_lshlrev_b32_e32 v3, 4, v3
	v_bfe_u32 v97, v0, 6, 1
	v_lshrrev_b32_e32 v1, 4, v0
	v_ashrrev_i32_e32 v96, 7, v0
	v_and_b32_e32 v98, 15, v0
	v_bfe_u32 v99, v0, 4, 2
	v_xor_b32_e32 v6, v6, v0
	v_and_b32_e32 v3, 0x70, v3
	v_bfe_u32 v0, v0, 1, 3
	s_mov_b64 s[0:1], 0x10000
	v_lshl_or_b32 v107, v2, 7, v3
	v_bitop3_b32 v1, v1, v0, 3 bitop3:0x6c
	v_lshlrev_b32_e32 v2, 7, v98
	v_bitop3_b32 v0, v99, v0, 4 bitop3:0x36
	v_lshl_add_u64 v[68:69], v[64:65], 0, s[0:1]
	v_lshl_add_u64 v[70:71], v[66:67], 0, s[0:1]
	s_mov_b64 s[0:1], 0x30000
	v_lshlrev_b32_e32 v6, 4, v6
	v_lshl_or_b32 v3, v96, 13, v2
	v_lshl_or_b32 v2, v97, 13, v2
	v_lshlrev_b32_e32 v0, 4, v0
	v_lshl_add_u64 v[72:73], v[64:65], 0, s[66:67]
	v_lshl_add_u64 v[74:75], v[66:67], 0, s[66:67]
	v_lshl_add_u64 v[76:77], v[64:65], 0, s[0:1]
	v_lshl_add_u64 v[78:79], v[66:67], 0, s[0:1]
	v_and_b32_e32 v6, 0x70, v6
	v_lshlrev_b32_e32 v1, 4, v1
	v_or_b32_e32 v110, v0, v3
	v_or_b32_e32 v111, v0, v2
	v_mov_b32_e32 v0, 0
	s_mov_b32 s0, 1
	v_lshl_or_b32 v105, v5, 7, v6
	v_or_b32_e32 v108, v1, v3
	v_or_b32_e32 v109, v1, v2
	s_waitcnt vmcnt(5)
	v_lshrrev_b32_e32 v135, 3, v130
	v_and_b32_e32 v141, 7, v130
	v_lshlrev_b32_e32 v135, 11, v135
	v_readfirstlane_b32 s98, v64
	v_readfirstlane_b32 s99, v65
	v_lshl_or_b32 v135, v141, 4, v135
	v_readfirstlane_b32 s20, v66
	v_readfirstlane_b32 s21, v67
	v_add_u32_e32 v136, 0x10000, v135
	v_add_u32_e32 v137, 0x20000, v135
	v_add_u32_e32 v138, 0x30000, v135
	v_mov_b32_e32 v1, v0
	v_mov_b32_e32 v2, v0
	v_mov_b32_e32 v3, v0
	v_mov_b32_e32 v4, v0
	v_mov_b32_e32 v5, v0
	v_mov_b32_e32 v6, v0
	v_mov_b32_e32 v7, v0
	v_mov_b32_e32 v20, v0
	v_mov_b32_e32 v21, v0
	v_mov_b32_e32 v22, v0
	v_mov_b32_e32 v23, v0
	v_mov_b32_e32 v8, v0
	v_mov_b32_e32 v9, v0
	v_mov_b32_e32 v10, v0
	v_mov_b32_e32 v11, v0
	v_mov_b32_e32 v12, v0
	v_mov_b32_e32 v13, v0
	v_mov_b32_e32 v14, v0
	v_mov_b32_e32 v15, v0
	v_mov_b32_e32 v16, v0
	v_mov_b32_e32 v17, v0
	v_mov_b32_e32 v18, v0
	v_mov_b32_e32 v19, v0
	v_mov_b32_e32 v24, v0
	v_mov_b32_e32 v25, v0
	v_mov_b32_e32 v26, v0
	v_mov_b32_e32 v27, v0
	v_mov_b32_e32 v28, v0
	v_mov_b32_e32 v29, v0
	v_mov_b32_e32 v30, v0
	v_mov_b32_e32 v31, v0
	v_mov_b32_e32 v32, v0
	v_mov_b32_e32 v33, v0
	v_mov_b32_e32 v34, v0
	v_mov_b32_e32 v35, v0
	v_mov_b32_e32 v36, v0
	v_mov_b32_e32 v37, v0
	v_mov_b32_e32 v38, v0
	v_mov_b32_e32 v39, v0
	v_mov_b32_e32 v40, v0
	v_mov_b32_e32 v41, v0
	v_mov_b32_e32 v42, v0
	v_mov_b32_e32 v43, v0
	v_mov_b32_e32 v44, v0
	v_mov_b32_e32 v45, v0
	v_mov_b32_e32 v46, v0
	v_mov_b32_e32 v47, v0
	v_mov_b32_e32 v48, v0
	v_mov_b32_e32 v49, v0
	v_mov_b32_e32 v50, v0
	v_mov_b32_e32 v51, v0
	v_mov_b32_e32 v52, v0
	v_mov_b32_e32 v53, v0
	v_mov_b32_e32 v54, v0
	v_mov_b32_e32 v55, v0
	v_mov_b32_e32 v56, v0
	v_mov_b32_e32 v57, v0
	v_mov_b32_e32 v58, v0
	v_mov_b32_e32 v59, v0
	v_mov_b32_e32 v60, v0
	v_mov_b32_e32 v61, v0
	v_mov_b32_e32 v62, v0
	v_mov_b32_e32 v63, v0
	v_readlane_b32 s49, v165, 43
	v_readlane_b32 s50, v165, 44
	v_readlane_b32 s51, v165, 45
	v_readlane_b32 s52, v165, 46
	v_readlane_b32 s53, v165, 47
	v_readlane_b32 s54, v165, 48
	v_readlane_b32 s55, v165, 49
	v_readlane_b32 s56, v165, 50
	v_readlane_b32 s57, v165, 51
	v_readlane_b32 s60, v165, 54
	v_readlane_b32 s61, v165, 55
	v_readlane_b32 s62, v165, 56
	v_readlane_b32 s63, v165, 57
	global_load_dwordx4 v[64:67], v135, s[98:99]
	global_load_dwordx4 v[68:71], v135, s[20:21]
	global_load_dwordx4 v[72:75], v136, s[98:99]
	global_load_dwordx4 v[76:79], v136, s[20:21]
	global_load_dwordx4 v[156:159], v137, s[98:99]
	global_load_dwordx4 v[160:163], v137, s[20:21]
	global_load_dwordx4 v[148:151], v138, s[98:99]
	global_load_dwordx4 v[152:155], v138, s[20:21]
	s_add_u32 s98, s98, 0x80
	s_addc_u32 s99, s99, 0
	s_add_u32 s20, s20, 0x80
	s_addc_u32 s21, s21, 0
; template <class Epi>
; __device__ __forceinline__ void gemm_tile64(const bf16_t* A, const bf16_t* Bt, int tm, int tn, const Epi& epi, char* smem, const float* ssq, int nparts) {
;     ...
;     auto gload = [&](int kt, Slab& sl) {
; #pragma unroll
;         for (int i = 0; i < 4; ++i) { sl.a[i] = *(const u32x4*)(Ap + (size_t)(32 * i) * K + kt * 64); sl.b[i] = *(const u32x4*)(Bp + (size_t)(32 * i) * K + kt * 64); }
;     };
;     auto sstore = [&](const Slab& sl) {
; #pragma unroll
;         for (int i = 0; i < 4; ++i) {
;             const int r = lrow + 32 * i;
;             *(u32x4*)(sA + r * 64 + ((lc8 ^ ((r >> 1) & 7)) * 8)) = sl.a[i];
;             const int rs = (r & 64) | (((r >> 2) & 3) << 4) | (((r >> 4) & 3) << 2) | (r & 3);
;             *(u32x4*)(sB + rs * 64 + ((lc8 ^ ((rs >> 1) & 7)) * 8)) = sl.b[i];
;         }
;     };
;     auto compute = [&]() {
; #pragma unroll
;         for (int ks = 0; ks < 2; ++ks) {
;             bf16x8 af[4], bfr[4];
; #pragma unroll
;             for (int m = 0; m < 4; ++m) { const int r = wr * 64 + m * 16 + fr; af[m] = *(const bf16x8*)(sA + r * 64 + (((ks * 4 + fq) ^ ((r >> 1) & 7)) * 8)); }
; #pragma unroll
;             for (int n = 0; n < 4; ++n) { const int r = wc * 64 + n * 16 + fr; bfr[n] = *(const bf16x8*)(sB + r * 64 + (((ks * 4 + fq) ^ ((r >> 1) & 7)) * 8)); }
; #pragma unroll
;             for (int m = 0; m < 4; ++m)
; #pragma unroll
;                 for (int n = 0; n < 4; ++n) acc[m][n] = __builtin_amdgcn_mfma_f32_16x16x32_bf16(bfr[n], af[m], acc[m][n], 0, 0, 0);
;         }
;     };
;     Slab s0;
;     gload(0, s0);
;     for (int kt = 0; kt < 16; ++kt) {
;         __syncthreads(); sstore(s0); __syncthreads();
;         gload(min(kt + 1, 15), s0);
;         compute();
;     }
;     __device__ __forceinline__ void operator()(const f32x4 (&acc)[4][4], int tm, int tn, int wr, int wc, int fr, int fq, const float* sRs) const {
;     ...
;             const int rl = wr * 64 + m * 16 + fr; const float rs = sRs[rl]; const size_t row = (size_t)tm * 128 + rl;
;             const f32x4 v0 = acc[m][0] * rs, v1 = acc[m][1] * rs, v2 = acc[m][2] * rs, v3 = acc[m][3] * rs;
;             if (col0 == F0) {
;                 const float* bf = p->b_forget + l * 8;
;                 f32x4 o0, o1;
; #pragma unroll
;                 for (int j = 0; j < 4; ++j) {
;                     const float z0 = v0[j] + bf[j], z1 = v1[j] + bf[4 + j];
.LBB0_376:
	s_waitcnt lgkmcnt(0)
	s_barrier
	s_waitcnt vmcnt(7)
	ds_write_b128 v100, v[64:67]
	s_waitcnt vmcnt(6)
	ds_write_b128 v101, v[68:71] offset:16384
	s_waitcnt vmcnt(5)
	ds_write_b128 v102, v[72:75]
	s_waitcnt vmcnt(4)
	ds_write_b128 v103, v[76:79] offset:16384
	s_waitcnt vmcnt(3)
	ds_write_b128 v104, v[156:159]
	s_waitcnt vmcnt(2)
	ds_write_b128 v105, v[160:163] offset:16384
	s_waitcnt vmcnt(1)
	ds_write_b128 v106, v[148:151]
	s_waitcnt vmcnt(0)
	ds_write_b128 v107, v[152:155] offset:16384
	s_add_i32 s0, s0, 1
	s_waitcnt lgkmcnt(0)
	s_barrier
	ds_read_b128 v[80:83], v109 offset:16384
	ds_read_b128 v[84:87], v109 offset:18432
	ds_read_b128 v[88:91], v108
	ds_read_b128 v[92:95], v108 offset:2048
	ds_read_b128 v[116:119], v109 offset:20480
	ds_read_b128 v[120:123], v109 offset:22528
	s_cmp_eq_u32 s0, 17
	s_cbranch_scc1 .Lgi_nopf
	global_load_dwordx4 v[64:67], v135, s[98:99]
	global_load_dwordx4 v[68:71], v135, s[20:21]
	global_load_dwordx4 v[72:75], v136, s[98:99]
	global_load_dwordx4 v[76:79], v136, s[20:21]
	global_load_dwordx4 v[156:159], v137, s[98:99]
	global_load_dwordx4 v[160:163], v137, s[20:21]
	global_load_dwordx4 v[148:151], v138, s[98:99]
	global_load_dwordx4 v[152:155], v138, s[20:21]
	s_add_u32 s98, s98, 0x80
	s_addc_u32 s99, s99, 0
	s_add_u32 s20, s20, 0x80
	s_addc_u32 s21, s21, 0
.Lgi_nopf:
	s_waitcnt lgkmcnt(3)
	v_mfma_f32_16x16x32_bf16 v[60:63], v[80:83], v[88:91], v[60:63]
	v_mfma_f32_16x16x32_bf16 v[56:59], v[84:87], v[88:91], v[56:59]
	s_waitcnt lgkmcnt(1)
	v_mfma_f32_16x16x32_bf16 v[52:55], v[116:119], v[88:91], v[52:55]
	s_waitcnt lgkmcnt(0)
	v_mfma_f32_16x16x32_bf16 v[48:51], v[120:123], v[88:91], v[48:51]
	v_mfma_f32_16x16x32_bf16 v[44:47], v[80:83], v[92:95], v[44:47]
	v_mfma_f32_16x16x32_bf16 v[40:43], v[84:87], v[92:95], v[40:43]
	v_mfma_f32_16x16x32_bf16 v[36:39], v[116:119], v[92:95], v[36:39]
	v_mfma_f32_16x16x32_bf16 v[32:35], v[120:123], v[92:95], v[32:35]
	ds_read_b128 v[88:91], v108 offset:4096
	ds_read_b128 v[92:95], v108 offset:6144
	s_waitcnt lgkmcnt(1)
	v_mfma_f32_16x16x32_bf16 v[28:31], v[80:83], v[88:91], v[28:31]
	v_mfma_f32_16x16x32_bf16 v[24:27], v[84:87], v[88:91], v[24:27]
	v_mfma_f32_16x16x32_bf16 v[16:19], v[116:119], v[88:91], v[16:19]
	v_mfma_f32_16x16x32_bf16 v[12:15], v[120:123], v[88:91], v[12:15]
	s_waitcnt lgkmcnt(0)
	v_mfma_f32_16x16x32_bf16 v[8:11], v[80:83], v[92:95], v[8:11]
	v_mfma_f32_16x16x32_bf16 v[20:23], v[84:87], v[92:95], v[20:23]
	ds_read_b128 v[80:83], v111 offset:16384
	ds_read_b128 v[84:87], v111 offset:18432
	v_mfma_f32_16x16x32_bf16 v[4:7], v[116:119], v[92:95], v[4:7]
	v_mfma_f32_16x16x32_bf16 v[0:3], v[120:123], v[92:95], v[0:3]
	ds_read_b128 v[88:91], v110
	ds_read_b128 v[92:95], v110 offset:2048
	ds_read_b128 v[116:119], v111 offset:20480
	ds_read_b128 v[120:123], v111 offset:22528
	s_waitcnt lgkmcnt(3)
	v_mfma_f32_16x16x32_bf16 v[60:63], v[80:83], v[88:91], v[60:63]
	v_mfma_f32_16x16x32_bf16 v[56:59], v[84:87], v[88:91], v[56:59]
	s_waitcnt lgkmcnt(1)
	v_mfma_f32_16x16x32_bf16 v[52:55], v[116:119], v[88:91], v[52:55]
	s_waitcnt lgkmcnt(0)
	v_mfma_f32_16x16x32_bf16 v[48:51], v[120:123], v[88:91], v[48:51]
	ds_read_b128 v[88:91], v110 offset:4096
	ds_read_b128 v[144:147], v110 offset:6144
	v_mfma_f32_16x16x32_bf16 v[44:47], v[80:83], v[92:95], v[44:47]
	v_mfma_f32_16x16x32_bf16 v[40:43], v[84:87], v[92:95], v[40:43]
	v_mfma_f32_16x16x32_bf16 v[36:39], v[116:119], v[92:95], v[36:39]
	v_mfma_f32_16x16x32_bf16 v[32:35], v[120:123], v[92:95], v[32:35]
	s_waitcnt lgkmcnt(1)
	v_mfma_f32_16x16x32_bf16 v[28:31], v[80:83], v[88:91], v[28:31]
	v_mfma_f32_16x16x32_bf16 v[24:27], v[84:87], v[88:91], v[24:27]
	v_mfma_f32_16x16x32_bf16 v[16:19], v[116:119], v[88:91], v[16:19]
	v_mfma_f32_16x16x32_bf16 v[12:15], v[120:123], v[88:91], v[12:15]
	s_waitcnt lgkmcnt(0)
	v_mfma_f32_16x16x32_bf16 v[8:11], v[80:83], v[144:147], v[8:11]
	v_mfma_f32_16x16x32_bf16 v[20:23], v[84:87], v[144:147], v[20:23]
	v_mfma_f32_16x16x32_bf16 v[4:7], v[116:119], v[144:147], v[4:7]
	v_mfma_f32_16x16x32_bf16 v[0:3], v[120:123], v[144:147], v[0:3]
	s_cmp_eq_u32 s0, 17
	s_cbranch_scc0 .LBB0_376
	s_mov_b32 s21, 0
	s_movk_i32 s20, 0x780
	s_mov_b32 s1, 15
	v_lshl_or_b32 v66, v96, 6, v98
	v_lshlrev_b32_e32 v72, 2, v66
	ds_read_b32 v70, v72 offset:32768
	s_lshl_b32 s0, s22, 7
	v_lshlrev_b32_e32 v64, 6, v97
	v_lshlrev_b32_e32 v65, 4, v99
	v_or3_b32 v64, v64, s0, v65
	s_lshl_b64 s[36:37], s[46:47], 7
	s_movk_i32 s0, 0x600
	v_ashrrev_i32_e32 v67, 31, v66
	v_cmp_eq_u32_e32 vcc, s0, v64
	v_lshl_add_u64 v[68:69], s[36:37], 0, v[66:67]
	s_waitcnt lgkmcnt(0)
	v_pk_mul_f32 v[62:63], v[62:63], v[70:71] op_sel_hi:[1,0]
	v_pk_mul_f32 v[60:61], v[60:61], v[70:71] op_sel_hi:[1,0]
	v_pk_mul_f32 v[58:59], v[58:59], v[70:71] op_sel_hi:[1,0]
	v_pk_mul_f32 v[56:57], v[56:57], v[70:71] op_sel_hi:[1,0]
	s_and_saveexec_b64 s[40:41], vcc
	s_cbranch_execz .LBB0_411
	global_load_dword v65, v113, s[44:45]
	global_load_dword v71, v113, s[44:45] offset:16
	s_waitcnt vmcnt(1)
	v_add_f32_e32 v65, v60, v65
	v_mul_f32_e64 v67, |v65|, s94
	v_exp_f32_e32 v73, v67
	s_nop 0
	v_cmp_ngt_f32_e64 s[0:1], s96, v73
	s_and_saveexec_b64 s[12:13], s[0:1]
	s_xor_b64 s[42:43], exec, s[12:13]
	s_cbranch_execz .LBB0_380
	v_add_f32_e32 v67, 1.0, v73
	v_cmp_gt_f32_e64 s[0:1], s7, v67
	s_mov_b32 s8, 0x3f317217
	s_nop 0
	v_cndmask_b32_e64 v73, 0, 32, s[0:1]
	v_ldexp_f32 v67, v67, v73
	v_log_f32_e32 v67, v67
	s_nop 0
	v_mul_f32_e32 v73, 0x3f317217, v67
	v_fma_f32 v73, v67, s8, -v73
	v_fmac_f32_e32 v73, 0x3377d1cf, v67
	s_mov_b32 s8, 0x7f800000
	v_fmac_f32_e32 v73, 0x3f317217, v67
	v_cmp_lt_f32_e64 s[38:39], |v67|, s8
	s_nop 1
	v_cndmask_b32_e64 v67, v67, v73, s[38:39]
	v_cndmask_b32_e64 v73, 0, v140, s[0:1]
	v_sub_f32_e32 v67, v67, v73
